# prep phase prologue: the 96 low-rank weight fragment loads issued back to back into separate registers, one wait, then the 48 bf16 packs
# baseline (speedup 1.0000x reference)
.LBB0_157:
	s_or_b64 exec, exec, s[42:43]
	s_waitcnt lgkmcnt(0)
	s_barrier
	s_mov_b32 s16, 0
	s_ashr_i32 s17, s16, 31
	v_mov_b32_e32 v52, v152
	s_lshl_b64 s[4:5], s[16:17], 3
	s_load_dwordx2 s[18:19], s[0:1], 0xe0
	s_add_u32 s14, s0, s4
	v_readfirstlane_b32 s6, v52
	s_mov_b32 s54, s38
	s_mov_b32 s55, s2
	s_addc_u32 s15, s1, s5
	s_ashr_i32 s20, s6, 1
	v_and_b32_e32 v53, 15, v52
	s_load_dwordx2 s[4:5], s[14:15], 0x38
	s_load_dwordx4 s[8:11], s[14:15], 0x48
	s_andn2_b32 s20, s20, 31
	v_or_b32_e32 v0, s20, v53
	v_lshrrev_b32_e32 v1, 1, v52
	v_and_b32_e32 v56, 24, v1
	v_ashrrev_i32_e32 v1, 31, v0
	v_lshlrev_b64 v[14:15], 2, v[0:1]
	v_mov_b32_e32 v0, 0
	v_lshlrev_b32_e32 v12, 10, v56
	s_waitcnt lgkmcnt(0)
	v_lshl_add_u64 v[16:17], s[4:5], 0, v[14:15]
	v_mov_b32_e32 v13, v0
	v_lshl_add_u64 v[10:11], v[16:17], 0, v[12:13]
	v_or_b32_e32 v2, 0x1000, v12
	v_mov_b32_e32 v3, v0
	v_or_b32_e32 v4, 0x1400, v12
	v_mov_b32_e32 v5, v0
	v_or_b32_e32 v6, 0x1800, v12
	v_mov_b32_e32 v7, v0
	v_or_b32_e32 v8, 0x1c00, v12
	v_mov_b32_e32 v9, v0
	v_lshl_add_u64 v[18:19], v[16:17], 0, v[2:3]
	v_lshl_add_u64 v[20:21], v[16:17], 0, v[4:5]
	v_lshl_add_u64 v[22:23], v[16:17], 0, v[6:7]
	v_lshl_add_u64 v[24:25], v[16:17], 0, v[8:9]
	global_load_dword v76, v[10:11], off offset:1024
	global_load_dword v77, v[22:23], off
	global_load_dword v78, v[18:19], off
	global_load_dword v79, v[10:11], off offset:2048
	global_load_dword v80, v[10:11], off
	global_load_dword v81, v[10:11], off offset:3072
	global_load_dword v82, v[20:21], off
	global_load_dword v83, v[24:25], off
	v_lshl_add_u64 v[34:35], s[8:9], 0, v[14:15]
	v_lshl_add_u64 v[38:39], v[34:35], 0, v[12:13]
	s_load_dwordx4 s[4:7], s[14:15], 0x88
	v_lshl_add_u64 v[22:23], v[34:35], 0, v[2:3]
	v_lshl_add_u64 v[24:25], v[34:35], 0, v[4:5]
	v_lshl_add_u64 v[26:27], v[34:35], 0, v[6:7]
	v_lshl_add_u64 v[28:29], v[34:35], 0, v[8:9]
	s_mov_b32 s8, 0x8000
	s_mov_b32 s9, 0x9000
	v_lshl_add_u64 v[16:17], v[16:17], 0, 64
	s_add_u32 s34, s18, s16
	s_addc_u32 s35, s19, s17
	global_load_dword v84, v[38:39], off offset:1024
	global_load_dword v85, v[26:27], off
	global_load_dword v86, v[22:23], off
	global_load_dword v87, v[38:39], off offset:2048
	global_load_dword v88, v[38:39], off
	global_load_dword v89, v[38:39], off offset:3072
	global_load_dword v90, v[24:25], off
	global_load_dword v91, v[28:29], off
	v_lshl_add_u64 v[40:41], s[10:11], 0, v[14:15]
	v_lshl_add_u64 v[42:43], v[40:41], 0, v[12:13]
	v_lshl_add_u64 v[26:27], v[40:41], 0, v[2:3]
	v_lshl_add_u64 v[28:29], v[40:41], 0, v[4:5]
	v_lshl_add_u64 v[30:31], v[40:41], 0, v[6:7]
	v_lshl_add_u64 v[32:33], v[40:41], 0, v[8:9]
	s_waitcnt lgkmcnt(0)
	v_lshl_add_u64 v[14:15], s[6:7], 0, v[14:15]
	v_lshl_add_u64 v[12:13], v[14:15], 0, v[12:13]
	global_load_dword v92, v[42:43], off offset:1024
	global_load_dword v93, v[30:31], off
	global_load_dword v94, v[26:27], off
	global_load_dword v95, v[42:43], off offset:2048
	global_load_dword v96, v[42:43], off
	global_load_dword v97, v[42:43], off offset:3072
	global_load_dword v98, v[28:29], off
	global_load_dword v99, v[32:33], off
	v_add_co_u32_e32 v46, vcc, s8, v42
	s_add_u32 s8, s34, 0x4d00000
	s_nop 0
	v_addc_co_u32_e32 v47, vcc, 0, v43, vcc
	v_add_co_u32_e32 v48, vcc, s9, v42
	s_addc_u32 s9, s35, 0
	s_nop 0
	v_addc_co_u32_e32 v49, vcc, 0, v43, vcc
	s_cmpk_lt_i32 s55, 0x400
	s_cselect_b64 s[6:7], -1, 0
	global_load_dword v100, v[46:47], off offset:1024
	global_load_dword v101, v[48:49], off offset:-4096
	global_load_dword v102, v[48:49], off offset:2048
	global_load_dword v103, v[48:49], off
	global_load_dword v104, v[46:47], off offset:3072
	global_load_dword v105, v[46:47], off offset:2048
	global_load_dword v106, v[48:49], off offset:1024
	global_load_dword v107, v[48:49], off offset:3072
	v_lshl_add_u64 v[36:37], v[14:15], 0, v[2:3]
	v_lshl_add_u64 v[44:45], v[14:15], 0, v[4:5]
	v_lshl_add_u64 v[50:51], v[14:15], 0, v[6:7]
	v_lshl_add_u64 v[54:55], v[14:15], 0, v[8:9]
	global_load_dword v108, v[12:13], off offset:1024
	global_load_dword v109, v[50:51], off
	global_load_dword v110, v[36:37], off
	global_load_dword v111, v[12:13], off offset:2048
	global_load_dword v112, v[12:13], off
	global_load_dword v113, v[12:13], off offset:3072
	global_load_dword v114, v[44:45], off
	global_load_dword v115, v[54:55], off
	v_or_b32_e32 v44, s20, v56
	v_or_b32_e32 v50, 1, v44
	v_mov_b32_e32 v37, v0
	v_lshlrev_b32_e32 v36, 2, v53
	v_or_b32_e32 v54, 2, v44
	v_or_b32_e32 v56, 3, v44
	v_or_b32_e32 v58, 4, v44
	v_or_b32_e32 v60, 5, v44
	v_or_b32_e32 v62, 6, v44
	v_or_b32_e32 v64, 7, v44
	v_ashrrev_i32_e32 v51, 31, v50
	v_ashrrev_i32_e32 v45, 31, v44
	v_ashrrev_i32_e32 v55, 31, v54
	v_ashrrev_i32_e32 v57, 31, v56
	v_ashrrev_i32_e32 v59, 31, v58
	v_ashrrev_i32_e32 v61, 31, v60
	v_ashrrev_i32_e32 v63, 31, v62
	v_ashrrev_i32_e32 v65, 31, v64
	v_lshlrev_b64 v[50:51], 7, v[50:51]
	v_lshl_add_u64 v[36:37], s[4:5], 0, v[36:37]
	v_lshlrev_b64 v[44:45], 7, v[44:45]
	v_lshlrev_b64 v[54:55], 7, v[54:55]
	v_lshlrev_b64 v[56:57], 7, v[56:57]
	v_lshlrev_b64 v[58:59], 7, v[58:59]
	v_lshlrev_b64 v[60:61], 7, v[60:61]
	v_lshlrev_b64 v[62:63], 7, v[62:63]
	v_lshlrev_b64 v[64:65], 7, v[64:65]
	v_lshl_add_u64 v[50:51], v[36:37], 0, v[50:51]
	v_lshl_add_u64 v[66:67], v[36:37], 0, v[44:45]
	v_lshl_add_u64 v[54:55], v[36:37], 0, v[54:55]
	v_lshl_add_u64 v[56:57], v[36:37], 0, v[56:57]
	v_lshl_add_u64 v[58:59], v[36:37], 0, v[58:59]
	v_lshl_add_u64 v[60:61], v[36:37], 0, v[60:61]
	v_lshl_add_u64 v[62:63], v[36:37], 0, v[62:63]
	v_lshl_add_u64 v[64:65], v[36:37], 0, v[64:65]
	v_lshl_add_u64 v[36:37], v[16:17], 0, v[2:3]
	v_lshl_add_u64 v[44:45], v[16:17], 0, v[4:5]
	s_movk_i32 s4, 0x1c0
	v_cmp_gt_i32_e64 s[4:5], s4, v52
	s_and_b64 s[10:11], s[4:5], s[6:7]
	s_xor_b64 s[10:11], s[10:11], -1
	global_load_dword v116, v[50:51], off
	global_load_dword v117, v[62:63], off
	global_load_dword v118, v[58:59], off
	global_load_dword v119, v[54:55], off
	global_load_dword v120, v[66:67], off
	global_load_dword v121, v[56:57], off
	global_load_dword v122, v[60:61], off
	global_load_dword v123, v[64:65], off
	v_lshl_add_u64 v[68:69], v[16:17], 0, v[6:7]
	v_lshl_add_u64 v[16:17], v[16:17], 0, v[8:9]
	global_load_dword v124, v[10:11], off offset:1088
	global_load_dword v125, v[68:69], off
	global_load_dword v126, v[36:37], off
	global_load_dword v127, v[10:11], off offset:2112
	global_load_dword v132, v[10:11], off offset:64
	global_load_dword v133, v[10:11], off offset:3136
	global_load_dword v134, v[44:45], off
	global_load_dword v135, v[16:17], off
	v_lshl_add_u64 v[10:11], v[34:35], 0, 64
	v_lshl_add_u64 v[16:17], v[10:11], 0, v[2:3]
	v_lshl_add_u64 v[44:45], v[10:11], 0, v[4:5]
	v_lshl_add_u64 v[68:69], v[10:11], 0, v[6:7]
	v_lshl_add_u64 v[10:11], v[10:11], 0, v[8:9]
	global_load_dword v136, v[38:39], off offset:1088
	global_load_dword v137, v[68:69], off
	global_load_dword v138, v[16:17], off
	global_load_dword v139, v[38:39], off offset:2112
	global_load_dword v140, v[38:39], off offset:64
	global_load_dword v141, v[38:39], off offset:3136
	global_load_dword v142, v[44:45], off
	global_load_dword v143, v[10:11], off
	v_lshl_add_u64 v[10:11], v[40:41], 0, 64
	v_lshl_add_u64 v[16:17], v[10:11], 0, v[2:3]
	v_lshl_add_u64 v[44:45], v[10:11], 0, v[4:5]
	v_lshl_add_u64 v[68:69], v[10:11], 0, v[6:7]
	v_lshl_add_u64 v[10:11], v[10:11], 0, v[8:9]
	global_load_dword v144, v[42:43], off offset:1088
	global_load_dword v145, v[68:69], off
	global_load_dword v146, v[16:17], off
	global_load_dword v147, v[42:43], off offset:2112
	global_load_dword v148, v[42:43], off offset:64
	global_load_dword v149, v[42:43], off offset:3136
	global_load_dword v150, v[44:45], off
	global_load_dword v151, v[10:11], off
	v_lshl_add_u64 v[10:11], v[14:15], 0, 64
	v_lshl_add_u64 v[2:3], v[10:11], 0, v[2:3]
	v_lshl_add_u64 v[4:5], v[10:11], 0, v[4:5]
	v_lshl_add_u64 v[6:7], v[10:11], 0, v[6:7]
	v_lshl_add_u64 v[8:9], v[10:11], 0, v[8:9]
	global_load_dword v155, v[46:47], off offset:1088
	global_load_dword v156, v[48:49], off offset:2112
	global_load_dword v157, v[48:49], off offset:64
	global_load_dword v158, v[46:47], off offset:2112
	global_load_dword v159, v[46:47], off offset:64
	global_load_dword v160, v[46:47], off offset:3136
	global_load_dword v161, v[48:49], off offset:1088
	global_load_dword v162, v[48:49], off offset:3136
	global_load_dword v163, v[12:13], off offset:1088
	global_load_dword v164, v[6:7], off
	global_load_dword v165, v[2:3], off
	global_load_dword v166, v[12:13], off offset:2112
	global_load_dword v167, v[12:13], off offset:64
	global_load_dword v168, v[12:13], off offset:3136
	global_load_dword v169, v[4:5], off
	global_load_dword v170, v[8:9], off
	global_load_dword v171, v[50:51], off offset:64
	global_load_dword v172, v[62:63], off offset:64
	global_load_dword v173, v[58:59], off offset:64
	global_load_dword v174, v[54:55], off offset:64
	global_load_dword v175, v[66:67], off offset:64
	global_load_dword v176, v[56:57], off offset:64
	global_load_dword v177, v[60:61], off offset:64
	global_load_dword v178, v[64:65], off offset:64
	v_lshlrev_b32_e32 v50, 1, v52
	s_waitcnt vmcnt(0)
	v_cvt_pk_bf16_f32 v18, v80, v76
	v_cvt_pk_bf16_f32 v19, v79, v81
	v_cvt_pk_bf16_f32 v20, v78, v82
	v_cvt_pk_bf16_f32 v21, v77, v83
	v_cvt_pk_bf16_f32 v22, v88, v84
	v_cvt_pk_bf16_f32 v23, v87, v89
	v_cvt_pk_bf16_f32 v24, v86, v90
	v_cvt_pk_bf16_f32 v25, v85, v91
	v_cvt_pk_bf16_f32 v26, v96, v92
	v_cvt_pk_bf16_f32 v27, v95, v97
	v_cvt_pk_bf16_f32 v28, v94, v98
	v_cvt_pk_bf16_f32 v29, v93, v99
	v_cvt_pk_bf16_f32 v30, v101, v100
	v_cvt_pk_bf16_f32 v31, v105, v104
	v_cvt_pk_bf16_f32 v32, v103, v106
	v_cvt_pk_bf16_f32 v33, v102, v107
	v_cvt_pk_bf16_f32 v1, v112, v108
	v_cvt_pk_bf16_f32 v1, v111, v113
	v_cvt_pk_bf16_f32 v1, v110, v114
	v_cvt_pk_bf16_f32 v1, v109, v115
	v_cvt_pk_bf16_f32 v1, v120, v116
	v_cvt_pk_bf16_f32 v1, v119, v121
	v_cvt_pk_bf16_f32 v1, v118, v122
	v_cvt_pk_bf16_f32 v1, v117, v123
	v_cvt_pk_bf16_f32 v34, v132, v124
	v_cvt_pk_bf16_f32 v35, v127, v133
	v_cvt_pk_bf16_f32 v36, v126, v134
	v_cvt_pk_bf16_f32 v37, v125, v135
	v_cvt_pk_bf16_f32 v38, v140, v136
	v_cvt_pk_bf16_f32 v39, v139, v141
	v_cvt_pk_bf16_f32 v40, v138, v142
	v_cvt_pk_bf16_f32 v41, v137, v143
	v_cvt_pk_bf16_f32 v42, v148, v144
	v_cvt_pk_bf16_f32 v43, v147, v149
	v_cvt_pk_bf16_f32 v44, v146, v150
	v_cvt_pk_bf16_f32 v45, v145, v151
	v_cvt_pk_bf16_f32 v46, v159, v155
	v_cvt_pk_bf16_f32 v47, v158, v160
	v_cvt_pk_bf16_f32 v48, v157, v161
	v_cvt_pk_bf16_f32 v49, v156, v162
	v_cvt_pk_bf16_f32 v1, v167, v163
	v_cvt_pk_bf16_f32 v1, v166, v168
	v_cvt_pk_bf16_f32 v1, v165, v169
	v_cvt_pk_bf16_f32 v1, v164, v170
	v_cvt_pk_bf16_f32 v1, v175, v171
	v_cvt_pk_bf16_f32 v1, v174, v176
	v_cvt_pk_bf16_f32 v1, v173, v177
	v_cvt_pk_bf16_f32 v1, v172, v178
	s_and_saveexec_b64 s[16:17], s[10:11]
	s_xor_b64 s[10:11], exec, s[16:17]
	v_lshlrev_b32_e32 v50, 1, v52
	s_or_saveexec_b64 s[10:11], s[10:11]
	v_mov_b32_e32 v1, v0
	v_mov_b32_e32 v2, v0
	v_mov_b32_e32 v3, v0
	v_mov_b32_e32 v4, v0
	v_mov_b32_e32 v5, v0
	v_mov_b32_e32 v6, v0
	v_mov_b32_e32 v7, v0
	v_mov_b32_e32 v8, v0
	v_mov_b32_e32 v9, v0
	v_mov_b32_e32 v10, v0
	v_mov_b32_e32 v11, v0
	v_mov_b32_e32 v12, v0
	v_mov_b32_e32 v13, v0
	v_mov_b32_e32 v14, v0
	v_mov_b32_e32 v15, v0
	v_mov_b32_e32 v16, v0
	s_xor_b64 exec, exec, s[10:11]
	s_cbranch_execz .LBB0_164
	s_lshl_b32 s16, s55, 4
	s_and_b32 s17, s55, 0xff
	s_cmp_lg_u32 s17, 0
	v_ashrrev_i32_e32 v51, 31, v50
	s_cbranch_scc0 .LBB0_338
	s_ashr_i32 s17, s16, 31
	s_lshl_b64 s[18:19], s[16:17], 11
	s_add_u32 s18, s8, s18
	s_addc_u32 s19, s9, s19
	v_lshl_add_u64 v[0:1], v[50:51], 1, s[18:19]
	global_load_dword v0, v[0:1], off offset:-2048
	s_cbranch_execnz .LBB0_163

.LBB0_1039:
	s_or_b64 exec, exec, s[42:43]
	s_waitcnt lgkmcnt(0)
	s_barrier
	s_mov_b32 s8, 0
	s_ashr_i32 s9, s8, 31
	s_lshl_b64 s[4:5], s[8:9], 3
	s_add_u32 s10, s0, s4
	v_mov_b32_e32 v68, v152
	s_mov_b32 s54, s38
	s_mov_b32 s55, s2
	s_addc_u32 s11, s1, s5
	s_load_dwordx2 s[14:15], s[0:1], 0xe0
	s_load_dwordx2 s[16:17], s[10:11], 0x38
	s_load_dwordx4 s[4:7], s[10:11], 0x48
	v_readfirstlane_b32 s22, v68
	v_and_b32_e32 v1, 15, v68
	v_lshrrev_b32_e32 v0, 1, v68
	s_waitcnt lgkmcnt(0)
	s_add_u32 s20, s16, 0x8000
	s_addc_u32 s21, s17, 0
	s_add_u32 s18, s4, 0x8000
	s_addc_u32 s19, s5, 0
	s_add_u32 s16, s6, 0x10000
	s_addc_u32 s17, s7, 0
	s_ashr_i32 s24, s22, 1
	s_andn2_b32 s24, s24, 31
	v_or_b32_e32 v12, s24, v1
	v_ashrrev_i32_e32 v13, 31, v12
	v_and_b32_e32 v42, 24, v0
	v_lshlrev_b64 v[14:15], 2, v[12:13]
	v_mov_b32_e32 v0, 0
	v_lshlrev_b32_e32 v10, 10, v42
	v_lshl_add_u64 v[16:17], s[20:21], 0, v[14:15]
	v_mov_b32_e32 v11, v0
	v_lshl_add_u64 v[18:19], v[16:17], 0, v[10:11]
	v_or_b32_e32 v2, 0x1000, v10
	v_mov_b32_e32 v3, v0
	v_or_b32_e32 v4, 0x1400, v10
	v_mov_b32_e32 v5, v0
	v_or_b32_e32 v6, 0x1800, v10
	v_mov_b32_e32 v7, v0
	v_or_b32_e32 v8, 0x1c00, v10
	v_mov_b32_e32 v9, v0
	v_lshl_add_u64 v[20:21], v[16:17], 0, v[2:3]
	v_lshl_add_u64 v[22:23], v[16:17], 0, v[4:5]
	v_lshl_add_u64 v[24:25], v[16:17], 0, v[6:7]
	v_lshl_add_u64 v[16:17], v[16:17], 0, v[8:9]
	global_load_dword v82, v[18:19], off offset:1024
	global_load_dword v83, v[24:25], off
	global_load_dword v84, v[20:21], off
	global_load_dword v85, v[18:19], off offset:2048
	global_load_dword v86, v[18:19], off
	global_load_dword v87, v[18:19], off offset:3072
	global_load_dword v88, v[22:23], off
	global_load_dword v89, v[16:17], off
	v_lshl_add_u64 v[16:17], s[18:19], 0, v[14:15]
	v_lshl_add_u64 v[22:23], v[16:17], 0, v[10:11]
	s_load_dwordx4 s[4:7], s[10:11], 0x88
	v_lshl_add_u64 v[24:25], v[16:17], 0, v[2:3]
	v_lshl_add_u64 v[26:27], v[16:17], 0, v[4:5]
	v_lshl_add_u64 v[28:29], v[16:17], 0, v[6:7]
	v_lshl_add_u64 v[16:17], v[16:17], 0, v[8:9]
	s_mov_b32 s22, 0x8000
	s_mov_b32 s23, 0x9000
	v_or_b32_e32 v12, 16, v12
	s_add_u32 s34, s14, s8
	s_addc_u32 s35, s15, s9
	s_add_u32 s8, s34, 0x4d00000
	s_addc_u32 s9, s35, 0
	s_cmpk_lt_i32 s55, 0x400
	global_load_dword v90, v[22:23], off offset:1024
	global_load_dword v91, v[28:29], off
	global_load_dword v92, v[24:25], off
	global_load_dword v93, v[22:23], off offset:2048
	global_load_dword v94, v[22:23], off
	global_load_dword v95, v[22:23], off offset:3072
	global_load_dword v96, v[26:27], off
	global_load_dword v97, v[16:17], off
	v_lshl_add_u64 v[16:17], s[16:17], 0, v[14:15]
	v_lshl_add_u64 v[26:27], v[16:17], 0, v[10:11]
	v_lshl_add_u64 v[28:29], v[16:17], 0, v[2:3]
	v_lshl_add_u64 v[30:31], v[16:17], 0, v[4:5]
	v_lshl_add_u64 v[32:33], v[16:17], 0, v[6:7]
	v_lshl_add_u64 v[16:17], v[16:17], 0, v[8:9]
	global_load_dword v98, v[26:27], off offset:1024
	global_load_dword v99, v[32:33], off
	global_load_dword v100, v[28:29], off
	global_load_dword v101, v[26:27], off offset:2048
	global_load_dword v102, v[26:27], off
	global_load_dword v103, v[26:27], off offset:3072
	global_load_dword v104, v[30:31], off
	global_load_dword v105, v[16:17], off
	v_add_co_u32_e32 v16, vcc, s22, v26
	s_nop 1
	v_addc_co_u32_e32 v17, vcc, 0, v27, vcc
	v_add_co_u32_e32 v30, vcc, s23, v26
	s_nop 0
	v_addc_co_u32_e32 v31, vcc, 0, v27, vcc
	global_load_dword v106, v[16:17], off offset:1024
	global_load_dword v107, v[30:31], off offset:-4096
	global_load_dword v108, v[30:31], off offset:2048
	global_load_dword v109, v[30:31], off
	global_load_dword v110, v[16:17], off offset:3072
	global_load_dword v111, v[16:17], off offset:2048
	global_load_dword v112, v[30:31], off offset:1024
	global_load_dword v113, v[30:31], off offset:3072
	s_waitcnt lgkmcnt(0)
	v_lshl_add_u64 v[16:17], s[6:7], 0, v[14:15]
	v_lshl_add_u64 v[14:15], v[16:17], 0, v[10:11]
	v_lshl_add_u64 v[34:35], v[16:17], 0, v[2:3]
	v_lshl_add_u64 v[36:37], v[16:17], 0, v[4:5]
	v_lshl_add_u64 v[38:39], v[16:17], 0, v[6:7]
	v_lshl_add_u64 v[40:41], v[16:17], 0, v[8:9]
	s_cselect_b64 s[6:7], -1, 0
	global_load_dword v114, v[14:15], off offset:1024
	global_load_dword v115, v[38:39], off
	global_load_dword v116, v[34:35], off
	global_load_dword v117, v[14:15], off offset:2048
	global_load_dword v118, v[14:15], off
	global_load_dword v119, v[14:15], off offset:3072
	global_load_dword v120, v[36:37], off
	global_load_dword v121, v[40:41], off
	v_or_b32_e32 v36, s24, v42
	v_or_b32_e32 v38, 1, v36
	v_mov_b32_e32 v35, v0
	v_lshlrev_b32_e32 v34, 2, v1
	v_or_b32_e32 v40, 2, v36
	v_or_b32_e32 v42, 3, v36
	v_or_b32_e32 v44, 4, v36
	v_or_b32_e32 v46, 5, v36
	v_or_b32_e32 v48, 6, v36
	v_or_b32_e32 v50, 7, v36
	v_ashrrev_i32_e32 v39, 31, v38
	v_lshl_add_u64 v[34:35], s[4:5], 0, v[34:35]
	v_ashrrev_i32_e32 v37, 31, v36
	v_ashrrev_i32_e32 v41, 31, v40
	v_ashrrev_i32_e32 v43, 31, v42
	v_ashrrev_i32_e32 v45, 31, v44
	v_ashrrev_i32_e32 v47, 31, v46
	v_ashrrev_i32_e32 v49, 31, v48
	v_ashrrev_i32_e32 v51, 31, v50
	v_lshlrev_b64 v[38:39], 7, v[38:39]
	v_lshlrev_b64 v[36:37], 7, v[36:37]
	v_lshlrev_b64 v[40:41], 7, v[40:41]
	v_lshlrev_b64 v[42:43], 7, v[42:43]
	v_lshlrev_b64 v[44:45], 7, v[44:45]
	v_lshlrev_b64 v[46:47], 7, v[46:47]
	v_lshlrev_b64 v[48:49], 7, v[48:49]
	v_lshlrev_b64 v[50:51], 7, v[50:51]
	v_lshl_add_u64 v[64:65], v[34:35], 0, v[38:39]
	v_lshl_add_u64 v[62:63], v[34:35], 0, v[36:37]
	v_lshl_add_u64 v[66:67], v[34:35], 0, v[40:41]
	v_lshl_add_u64 v[70:71], v[34:35], 0, v[42:43]
	v_lshl_add_u64 v[72:73], v[34:35], 0, v[44:45]
	v_lshl_add_u64 v[74:75], v[34:35], 0, v[46:47]
	v_lshl_add_u64 v[76:77], v[34:35], 0, v[48:49]
	v_lshl_add_u64 v[78:79], v[34:35], 0, v[50:51]
	v_lshl_add_u64 v[38:39], s[20:21], 0, v[10:11]
	s_movk_i32 s4, 0x1c0
	v_cmp_gt_i32_e64 s[4:5], s4, v68
	s_and_b64 s[14:15], s[4:5], s[6:7]
	s_xor_b64 s[14:15], s[14:15], -1
	global_load_dword v122, v[64:65], off
	global_load_dword v123, v[76:77], off
	global_load_dword v124, v[72:73], off
	global_load_dword v125, v[66:67], off
	global_load_dword v126, v[62:63], off
	global_load_dword v127, v[70:71], off
	global_load_dword v132, v[74:75], off
	global_load_dword v133, v[78:79], off
	v_ashrrev_i32_e32 v13, 31, v12
	v_lshlrev_b64 v[12:13], 2, v[12:13]
	v_lshl_add_u64 v[40:41], s[20:21], 0, v[12:13]
	v_lshl_add_u64 v[44:45], v[40:41], 0, v[10:11]
	v_lshl_add_u64 v[42:43], v[38:39], 0, v[12:13]
	v_lshl_add_u64 v[46:47], v[40:41], 0, v[2:3]
	v_lshl_add_u64 v[48:49], v[40:41], 0, v[4:5]
	v_lshl_add_u64 v[50:51], v[40:41], 0, v[6:7]
	v_lshl_add_u64 v[52:53], v[40:41], 0, v[8:9]
	global_load_dword v134, v[44:45], off offset:1024
	global_load_dword v135, v[50:51], off
	global_load_dword v136, v[46:47], off
	global_load_dword v137, v[44:45], off offset:2048
	global_load_dword v138, v[42:43], off
	global_load_dword v139, v[44:45], off offset:3072
	global_load_dword v140, v[48:49], off
	global_load_dword v141, v[52:53], off
	v_lshl_add_u64 v[44:45], s[18:19], 0, v[12:13]
	v_lshl_add_u64 v[42:43], s[18:19], 0, v[10:11]
	v_lshl_add_u64 v[48:49], v[44:45], 0, v[10:11]
	v_lshl_add_u64 v[46:47], v[42:43], 0, v[12:13]
	v_lshl_add_u64 v[50:51], v[44:45], 0, v[2:3]
	v_lshl_add_u64 v[52:53], v[44:45], 0, v[4:5]
	v_lshl_add_u64 v[54:55], v[44:45], 0, v[6:7]
	v_lshl_add_u64 v[56:57], v[44:45], 0, v[8:9]
	global_load_dword v142, v[48:49], off offset:1024
	global_load_dword v143, v[54:55], off
	global_load_dword v144, v[50:51], off
	global_load_dword v145, v[48:49], off offset:2048
	global_load_dword v146, v[46:47], off
	global_load_dword v147, v[48:49], off offset:3072
	global_load_dword v148, v[52:53], off
	global_load_dword v149, v[56:57], off
	v_lshl_add_u64 v[48:49], s[16:17], 0, v[12:13]
	v_lshl_add_u64 v[46:47], s[16:17], 0, v[10:11]
	v_lshl_add_u64 v[10:11], v[48:49], 0, v[10:11]
	v_lshl_add_u64 v[12:13], v[46:47], 0, v[12:13]
	v_lshl_add_u64 v[50:51], v[48:49], 0, v[2:3]
	v_lshl_add_u64 v[52:53], v[48:49], 0, v[4:5]
	v_lshl_add_u64 v[54:55], v[48:49], 0, v[6:7]
	v_lshl_add_u64 v[56:57], v[48:49], 0, v[8:9]
	global_load_dword v150, v[10:11], off offset:1024
	global_load_dword v151, v[54:55], off
	global_load_dword v155, v[50:51], off
	global_load_dword v156, v[10:11], off offset:2048
	global_load_dword v157, v[12:13], off
	global_load_dword v158, v[10:11], off offset:3072
	global_load_dword v159, v[52:53], off
	global_load_dword v160, v[56:57], off
	v_add_co_u32_e32 v10, vcc, s22, v12
	s_nop 0
	v_addc_co_u32_e32 v11, vcc, 0, v13, vcc
	v_add_co_u32_e32 v12, vcc, s23, v12
	v_addc_co_u32_e32 v13, vcc, 0, v13, vcc
	global_load_dword v161, v[10:11], off offset:1024
	global_load_dword v162, v[12:13], off offset:-4096
	global_load_dword v163, v[12:13], off offset:2048
	global_load_dword v164, v[12:13], off
	global_load_dword v165, v[10:11], off offset:3072
	global_load_dword v166, v[10:11], off offset:2048
	global_load_dword v167, v[12:13], off offset:1024
	global_load_dword v168, v[12:13], off offset:3072
	v_lshl_add_u64 v[10:11], v[16:17], 0, 64
	v_lshl_add_u64 v[2:3], v[10:11], 0, v[2:3]
	v_lshl_add_u64 v[4:5], v[10:11], 0, v[4:5]
	v_lshl_add_u64 v[6:7], v[10:11], 0, v[6:7]
	v_lshl_add_u64 v[8:9], v[10:11], 0, v[8:9]
	global_load_dword v169, v[14:15], off offset:1088
	global_load_dword v170, v[6:7], off
	global_load_dword v171, v[2:3], off
	global_load_dword v172, v[14:15], off offset:2112
	global_load_dword v173, v[14:15], off offset:64
	global_load_dword v174, v[14:15], off offset:3136
	global_load_dword v175, v[4:5], off
	global_load_dword v176, v[8:9], off
	global_load_dword v177, v[64:65], off offset:64
	global_load_dword v178, v[76:77], off offset:64
	global_load_dword v179, v[72:73], off offset:64
	global_load_dword v180, v[66:67], off offset:64
	global_load_dword v181, v[62:63], off offset:64
	global_load_dword v182, v[70:71], off offset:64
	global_load_dword v183, v[74:75], off offset:64
	global_load_dword v184, v[78:79], off offset:64
	v_lshlrev_b32_e32 v66, 1, v68
	s_waitcnt vmcnt(0)
	v_cvt_pk_bf16_f32 v18, v86, v82
	v_cvt_pk_bf16_f32 v19, v85, v87
	v_cvt_pk_bf16_f32 v20, v84, v88
	v_cvt_pk_bf16_f32 v21, v83, v89
	v_cvt_pk_bf16_f32 v22, v94, v90
	v_cvt_pk_bf16_f32 v23, v93, v95
	v_cvt_pk_bf16_f32 v24, v92, v96
	v_cvt_pk_bf16_f32 v25, v91, v97
	v_cvt_pk_bf16_f32 v26, v102, v98
	v_cvt_pk_bf16_f32 v27, v101, v103
	v_cvt_pk_bf16_f32 v28, v100, v104
	v_cvt_pk_bf16_f32 v29, v99, v105
	v_cvt_pk_bf16_f32 v30, v107, v106
	v_cvt_pk_bf16_f32 v31, v111, v110
	v_cvt_pk_bf16_f32 v32, v109, v112
	v_cvt_pk_bf16_f32 v33, v108, v113
	v_cvt_pk_bf16_f32 v34, v118, v114
	v_cvt_pk_bf16_f32 v35, v117, v119
	v_cvt_pk_bf16_f32 v36, v116, v120
	v_cvt_pk_bf16_f32 v37, v115, v121
	v_cvt_pk_bf16_f32 v38, v126, v122
	v_cvt_pk_bf16_f32 v39, v125, v127
	v_cvt_pk_bf16_f32 v40, v124, v132
	v_cvt_pk_bf16_f32 v41, v123, v133
	v_cvt_pk_bf16_f32 v42, v138, v134
	v_cvt_pk_bf16_f32 v43, v137, v139
	v_cvt_pk_bf16_f32 v44, v136, v140
	v_cvt_pk_bf16_f32 v45, v135, v141
	v_cvt_pk_bf16_f32 v46, v146, v142
	v_cvt_pk_bf16_f32 v47, v145, v147
	v_cvt_pk_bf16_f32 v48, v144, v148
	v_cvt_pk_bf16_f32 v49, v143, v149
	v_cvt_pk_bf16_f32 v50, v157, v150
	v_cvt_pk_bf16_f32 v51, v156, v158
	v_cvt_pk_bf16_f32 v52, v155, v159
	v_cvt_pk_bf16_f32 v53, v151, v160
	v_cvt_pk_bf16_f32 v54, v162, v161
	v_cvt_pk_bf16_f32 v55, v166, v165
	v_cvt_pk_bf16_f32 v56, v164, v167
	v_cvt_pk_bf16_f32 v57, v163, v168
	v_cvt_pk_bf16_f32 v58, v173, v169
	v_cvt_pk_bf16_f32 v59, v172, v174
	v_cvt_pk_bf16_f32 v60, v171, v175
	v_cvt_pk_bf16_f32 v61, v170, v176
	v_cvt_pk_bf16_f32 v62, v181, v177
	v_cvt_pk_bf16_f32 v63, v180, v182
	v_cvt_pk_bf16_f32 v64, v179, v183
	v_cvt_pk_bf16_f32 v65, v178, v184
	s_and_saveexec_b64 s[16:17], s[14:15]
	s_xor_b64 s[14:15], exec, s[16:17]
	v_lshlrev_b32_e32 v66, 1, v68
	s_or_saveexec_b64 s[14:15], s[14:15]
	v_mov_b32_e32 v1, v0
	v_mov_b32_e32 v2, v0
	v_mov_b32_e32 v3, v0
	v_mov_b32_e32 v4, v0
	v_mov_b32_e32 v5, v0
	v_mov_b32_e32 v6, v0
	v_mov_b32_e32 v7, v0
	v_mov_b32_e32 v8, v0
	v_mov_b32_e32 v9, v0
	v_mov_b32_e32 v10, v0
	v_mov_b32_e32 v11, v0
	v_mov_b32_e32 v12, v0
	v_mov_b32_e32 v13, v0
	v_mov_b32_e32 v14, v0
	v_mov_b32_e32 v15, v0
	v_mov_b32_e32 v16, v0
	s_xor_b64 exec, exec, s[14:15]
	s_cbranch_execz .LBB0_1046
	s_lshl_b32 s16, s55, 4
	s_and_b32 s17, s55, 0xff
	s_cmp_lg_u32 s17, 0
	v_ashrrev_i32_e32 v67, 31, v66
	s_cbranch_scc0 .LBB0_1220
	s_ashr_i32 s17, s16, 31
	s_lshl_b64 s[18:19], s[16:17], 11
	s_add_u32 s18, s8, s18
	s_addc_u32 s19, s9, s19
	v_lshl_add_u64 v[0:1], v[66:67], 1, s[18:19]
	global_load_dword v0, v[0:1], off offset:-2048
	s_cbranch_execnz .LBB0_1045
